# pp_v26 + IDX: the per-unit L1 invalidate (all 8 waves) replaced by sc1 (L1-bypass) loads for the wave's own score-row read-back
# speedup vs baseline: 1.0117x; 1.0117x over previous
.LBB0_579:
	s_waitcnt vmcnt(0)
	s_cmp_lt_u32 s33, 64
	s_mov_b64 s[14:15], -1
	s_cbranch_scc1 .LBB0_698
	s_lshr_b32 s14, s33, 1
	s_add_i32 s2, s42, s31
	v_cmp_ge_u32_e64 s[14:15], s14, v176
	s_mov_b32 s43, 0
	s_branch .LBB0_582

.LBB0_582:
	s_add_i32 s20, s2, s43
	v_cmp_ge_u32_e32 vcc, s20, v136
	v_mov_b32_e32 v1, 0
	v_mov_b32_e32 v3, 0
	v_mov_b32_e32 v4, 0
	v_mov_b32_e32 v5, 0
	v_mov_b32_e32 v6, 0
	v_mov_b32_e32 v7, 0
	v_mov_b32_e32 v8, 0
	v_mov_b32_e32 v9, 0
	v_mov_b32_e32 v11, 0
	v_mov_b32_e32 v19, 0
	v_mov_b32_e32 v20, 0
	v_mov_b32_e32 v21, 0
	v_mov_b32_e32 v22, 0
	v_mov_b32_e32 v23, 0
	v_mov_b32_e32 v24, 0
	v_mov_b32_e32 v25, 0
	v_mov_b32_e32 v2, 0
	v_mov_b32_e32 v12, 0
	v_mov_b32_e32 v13, 0
	v_mov_b32_e32 v14, 0
	v_mov_b32_e32 v15, 0
	v_mov_b32_e32 v16, 0
	v_mov_b32_e32 v17, 0
	v_mov_b32_e32 v18, 0
	v_mov_b32_e32 v26, 0
	v_mov_b32_e32 v27, 0
	v_mov_b32_e32 v29, 0
	v_mov_b32_e32 v30, 0
	v_mov_b32_e32 v31, 0
	v_mov_b32_e32 v32, 0
	v_mov_b32_e32 v33, 0
	v_mov_b32_e32 v34, 0
	v_mov_b32_e32 v35, 0
	s_and_saveexec_b64 s[16:17], vcc
	s_cbranch_execz .LBB0_584
	s_or_b32 s26, s43, s31
	s_mov_b32 s27, s21
	s_lshl_b64 s[26:27], s[26:27], 13
	v_lshl_add_u64 v[2:3], v[138:139], 0, s[26:27]
	global_load_dwordx4 v[4:7], v[2:3], off sc1
	global_load_dwordx4 v[8:11], v[2:3], off offset:16 sc1
	global_load_dwordx4 v[12:15], v[2:3], off offset:32 sc1
	global_load_dwordx4 v[24:27], v[2:3], off offset:48 sc1
	global_load_dwordx4 v[28:31], v[2:3], off offset:64 sc1
	global_load_dwordx4 v[32:35], v[2:3], off offset:80 sc1
	global_load_dwordx4 v[36:39], v[2:3], off offset:112 sc1
	global_load_dwordx4 v[40:43], v[2:3], off offset:96 sc1
	s_waitcnt vmcnt(7)
	v_lshrrev_b32_e32 v2, 15, v4
	v_lshrrev_b32_e32 v3, 15, v5
	v_lshrrev_b32_e32 v16, 15, v6
	v_lshrrev_b32_e32 v17, 15, v7
	s_waitcnt vmcnt(6)
	v_lshrrev_b32_e32 v18, 15, v8
	v_lshrrev_b32_e32 v19, 15, v9
	v_lshrrev_b32_e32 v20, 15, v10
	v_and_b32_e32 v2, 0x10001, v2
	v_and_b32_e32 v3, 0x10001, v3
	v_and_b32_e32 v16, 0x10001, v16
	v_and_b32_e32 v17, 0x10001, v17
	v_and_b32_e32 v18, 0x10001, v18
	v_and_b32_e32 v19, 0x10001, v19
	v_and_b32_e32 v20, 0x10001, v20
	v_mul_u32_u24_e32 v2, 0x7fff, v2
	v_mul_u32_u24_e32 v53, 0x7fff, v3
	v_mul_u32_u24_e32 v16, 0x7fff, v16
	v_mul_u32_u24_e32 v17, 0x7fff, v17
	v_mul_u32_u24_e32 v18, 0x7fff, v18
	v_mul_u32_u24_e32 v19, 0x7fff, v19
	v_mul_u32_u24_e32 v20, 0x7fff, v20
	s_waitcnt vmcnt(5)
	v_lshrrev_b32_e32 v22, 15, v12
	v_lshrrev_b32_e32 v45, 15, v15
	v_bitop3_b32 v3, v2, v4, s41 bitop3:0x36
	v_bitop3_b32 v4, v53, v5, s41 bitop3:0x36
	v_bitop3_b32 v5, v16, v6, s41 bitop3:0x36
	v_bitop3_b32 v6, v17, v7, s41 bitop3:0x36
	v_bitop3_b32 v7, v18, v8, s41 bitop3:0x36
	v_bitop3_b32 v8, v19, v9, s41 bitop3:0x36
	v_bitop3_b32 v9, v20, v10, s41 bitop3:0x36
	s_waitcnt vmcnt(3)
	v_lshrrev_b32_e32 v10, 15, v31
	v_and_b32_e32 v22, 0x10001, v22
	v_and_b32_e32 v45, 0x10001, v45
	v_and_b32_e32 v10, 0x10001, v10
	v_mul_u32_u24_e32 v22, 0x7fff, v22
	v_mul_u32_u24_e32 v45, 0x7fff, v45
	v_mul_u32_u24_e32 v10, 0x7fff, v10
	v_bitop3_b32 v19, v22, v12, s41 bitop3:0x36
	v_bitop3_b32 v22, v45, v15, s41 bitop3:0x36
	v_bitop3_b32 v15, v10, v31, s41 bitop3:0x36
	s_waitcnt vmcnt(2)
	v_lshrrev_b32_e32 v10, 15, v32
	v_and_b32_e32 v10, 0x10001, v10
	v_mul_u32_u24_e32 v10, 0x7fff, v10
	v_bitop3_b32 v16, v10, v32, s41 bitop3:0x36
	v_lshrrev_b32_e32 v10, 15, v33
	v_and_b32_e32 v10, 0x10001, v10
	v_mul_u32_u24_e32 v10, 0x7fff, v10
	v_bitop3_b32 v17, v10, v33, s41 bitop3:0x36
	v_lshrrev_b32_e32 v10, 15, v34
	v_and_b32_e32 v10, 0x10001, v10
	v_mul_u32_u24_e32 v10, 0x7fff, v10
	v_lshrrev_b32_e32 v23, 15, v13
	v_lshrrev_b32_e32 v46, 15, v24
	v_lshrrev_b32_e32 v47, 15, v25
	v_lshrrev_b32_e32 v48, 15, v26
	v_bitop3_b32 v18, v10, v34, s41 bitop3:0x36
	v_lshrrev_b32_e32 v10, 15, v35
	v_and_b32_e32 v23, 0x10001, v23
	v_and_b32_e32 v46, 0x10001, v46
	v_and_b32_e32 v47, 0x10001, v47
	v_and_b32_e32 v48, 0x10001, v48
	v_and_b32_e32 v10, 0x10001, v10
	v_mul_u32_u24_e32 v23, 0x7fff, v23
	v_mul_u32_u24_e32 v46, 0x7fff, v46
	v_mul_u32_u24_e32 v47, 0x7fff, v47
	v_mul_u32_u24_e32 v48, 0x7fff, v48
	v_mul_u32_u24_e32 v10, 0x7fff, v10
	v_lshrrev_b32_e32 v49, 15, v27
	v_bitop3_b32 v20, v23, v13, s41 bitop3:0x36
	v_bitop3_b32 v23, v46, v24, s41 bitop3:0x36
	v_bitop3_b32 v24, v47, v25, s41 bitop3:0x36
	v_bitop3_b32 v25, v48, v26, s41 bitop3:0x36
	v_bitop3_b32 v26, v10, v35, s41 bitop3:0x36
	s_waitcnt vmcnt(0)
	v_lshrrev_b32_e32 v10, 15, v40
	v_and_b32_e32 v49, 0x10001, v49
	v_and_b32_e32 v10, 0x10001, v10
	v_mul_u32_u24_e32 v49, 0x7fff, v49
	v_mul_u32_u24_e32 v10, 0x7fff, v10
	v_lshrrev_b32_e32 v51, 15, v29
	v_bitop3_b32 v2, v49, v27, s41 bitop3:0x36
	v_bitop3_b32 v27, v10, v40, s41 bitop3:0x36
	v_lshrrev_b32_e32 v10, 15, v41
	v_and_b32_e32 v51, 0x10001, v51
	v_and_b32_e32 v10, 0x10001, v10
	v_mul_u32_u24_e32 v51, 0x7fff, v51
	v_mul_u32_u24_e32 v10, 0x7fff, v10
	v_lshrrev_b32_e32 v21, 15, v11
	v_lshrrev_b32_e32 v44, 15, v14
	v_lshrrev_b32_e32 v52, 15, v30
	v_bitop3_b32 v13, v51, v29, s41 bitop3:0x36
	v_bitop3_b32 v29, v10, v41, s41 bitop3:0x36
	v_lshrrev_b32_e32 v10, 15, v42
	v_and_b32_e32 v21, 0x10001, v21
	v_and_b32_e32 v44, 0x10001, v44
	v_and_b32_e32 v52, 0x10001, v52
	v_and_b32_e32 v10, 0x10001, v10
	v_mul_u32_u24_e32 v21, 0x7fff, v21
	v_mul_u32_u24_e32 v44, 0x7fff, v44
	v_mul_u32_u24_e32 v52, 0x7fff, v52
	v_mul_u32_u24_e32 v10, 0x7fff, v10
	v_bitop3_b32 v11, v21, v11, s41 bitop3:0x36
	v_bitop3_b32 v21, v44, v14, s41 bitop3:0x36
	v_bitop3_b32 v14, v52, v30, s41 bitop3:0x36
	v_bitop3_b32 v30, v10, v42, s41 bitop3:0x36
	v_lshrrev_b32_e32 v10, 15, v43
	v_and_b32_e32 v10, 0x10001, v10
	v_mul_u32_u24_e32 v10, 0x7fff, v10
	v_bitop3_b32 v31, v10, v43, s41 bitop3:0x36
	v_lshrrev_b32_e32 v10, 15, v36
	v_and_b32_e32 v10, 0x10001, v10
	v_mul_u32_u24_e32 v10, 0x7fff, v10
	v_bitop3_b32 v32, v10, v36, s41 bitop3:0x36
	v_lshrrev_b32_e32 v10, 15, v37
	v_and_b32_e32 v10, 0x10001, v10
	v_mul_u32_u24_e32 v10, 0x7fff, v10
	v_bitop3_b32 v33, v10, v37, s41 bitop3:0x36
	v_lshrrev_b32_e32 v10, 15, v38
	v_and_b32_e32 v10, 0x10001, v10
	v_mul_u32_u24_e32 v10, 0x7fff, v10
	v_lshrrev_b32_e32 v50, 15, v28
	v_bitop3_b32 v34, v10, v38, s41 bitop3:0x36
	v_lshrrev_b32_e32 v10, 15, v39
	v_and_b32_e32 v50, 0x10001, v50
	v_and_b32_e32 v10, 0x10001, v10
	v_mul_u32_u24_e32 v50, 0x7fff, v50
	v_mul_u32_u24_e32 v10, 0x7fff, v10
	v_bitop3_b32 v12, v50, v28, s41 bitop3:0x36
	v_bitop3_b32 v35, v10, v39, s41 bitop3:0x36

.LBB0_701:
	s_add_i32 s20, s2, s33
	v_cmp_ge_u32_e32 vcc, s20, v162
	v_mov_b32_e32 v1, 0
	v_mov_b32_e32 v2, 0
	v_mov_b32_e32 v3, 0
	v_mov_b32_e32 v4, 0
	v_mov_b32_e32 v5, 0
	v_mov_b32_e32 v6, 0
	v_mov_b32_e32 v7, 0
	v_mov_b32_e32 v8, 0
	v_mov_b32_e32 v9, 0
	v_mov_b32_e32 v10, 0
	v_mov_b32_e32 v11, 0
	v_mov_b32_e32 v12, 0
	v_mov_b32_e32 v13, 0
	v_mov_b32_e32 v14, 0
	v_mov_b32_e32 v15, 0
	v_mov_b32_e32 v16, 0
	v_mov_b32_e32 v17, 0
	s_and_saveexec_b64 s[16:17], vcc
	s_cbranch_execz .LBB0_703
	s_or_b32 s26, s33, s31
	s_mov_b32 s27, s21
	s_lshl_b64 s[26:27], s[26:27], 13
	v_lshl_add_u64 v[14:15], v[142:143], 0, s[26:27]
	global_load_dwordx4 v[2:5], v[14:15], off sc1
	global_load_dwordx4 v[6:9], v[14:15], off offset:16 sc1
	global_load_dwordx4 v[10:13], v[14:15], off offset:32 sc1
	s_nop 0
	global_load_dwordx4 v[14:17], v[14:15], off offset:48 sc1
	s_waitcnt vmcnt(3)
	v_lshrrev_b32_e32 v18, 15, v2
	v_lshrrev_b32_e32 v19, 15, v3
	v_lshrrev_b32_e32 v20, 15, v4
	v_lshrrev_b32_e32 v21, 15, v5
	s_waitcnt vmcnt(2)
	v_lshrrev_b32_e32 v22, 15, v6
	v_lshrrev_b32_e32 v23, 15, v7
	v_lshrrev_b32_e32 v24, 15, v8
	v_lshrrev_b32_e32 v25, 15, v9
	s_waitcnt vmcnt(1)
	v_lshrrev_b32_e32 v26, 15, v10
	v_lshrrev_b32_e32 v27, 15, v11
	v_lshrrev_b32_e32 v28, 15, v12
	v_lshrrev_b32_e32 v29, 15, v13
	s_waitcnt vmcnt(0)
	v_lshrrev_b32_e32 v30, 15, v14
	v_lshrrev_b32_e32 v31, 15, v15
	v_lshrrev_b32_e32 v32, 15, v16
	v_lshrrev_b32_e32 v33, 15, v17
	v_and_b32_e32 v18, 0x10001, v18
	v_and_b32_e32 v19, 0x10001, v19
	v_and_b32_e32 v20, 0x10001, v20
	v_and_b32_e32 v21, 0x10001, v21
	v_and_b32_e32 v22, 0x10001, v22
	v_and_b32_e32 v23, 0x10001, v23
	v_and_b32_e32 v24, 0x10001, v24
	v_and_b32_e32 v25, 0x10001, v25
	v_and_b32_e32 v26, 0x10001, v26
	v_and_b32_e32 v27, 0x10001, v27
	v_and_b32_e32 v28, 0x10001, v28
	v_and_b32_e32 v29, 0x10001, v29
	v_and_b32_e32 v30, 0x10001, v30
	v_and_b32_e32 v31, 0x10001, v31
	v_and_b32_e32 v32, 0x10001, v32
	v_and_b32_e32 v33, 0x10001, v33
	v_mul_u32_u24_e32 v18, 0x7fff, v18
	v_mul_u32_u24_e32 v19, 0x7fff, v19
	v_mul_u32_u24_e32 v20, 0x7fff, v20
	v_mul_u32_u24_e32 v21, 0x7fff, v21
	v_mul_u32_u24_e32 v22, 0x7fff, v22
	v_mul_u32_u24_e32 v23, 0x7fff, v23
	v_mul_u32_u24_e32 v24, 0x7fff, v24
	v_mul_u32_u24_e32 v25, 0x7fff, v25
	v_mul_u32_u24_e32 v26, 0x7fff, v26
	v_mul_u32_u24_e32 v27, 0x7fff, v27
	v_mul_u32_u24_e32 v28, 0x7fff, v28
	v_mul_u32_u24_e32 v29, 0x7fff, v29
	v_mul_u32_u24_e32 v30, 0x7fff, v30
	v_mul_u32_u24_e32 v31, 0x7fff, v31
	v_mul_u32_u24_e32 v32, 0x7fff, v32
	v_mul_u32_u24_e32 v33, 0x7fff, v33
	v_bitop3_b32 v2, v18, v2, s41 bitop3:0x36
	v_bitop3_b32 v3, v19, v3, s41 bitop3:0x36
	v_bitop3_b32 v4, v20, v4, s41 bitop3:0x36
	v_bitop3_b32 v5, v21, v5, s41 bitop3:0x36
	v_bitop3_b32 v6, v22, v6, s41 bitop3:0x36
	v_bitop3_b32 v7, v23, v7, s41 bitop3:0x36
	v_bitop3_b32 v8, v24, v8, s41 bitop3:0x36
	v_bitop3_b32 v9, v25, v9, s41 bitop3:0x36
	v_bitop3_b32 v10, v26, v10, s41 bitop3:0x36
	v_bitop3_b32 v11, v27, v11, s41 bitop3:0x36
	v_bitop3_b32 v12, v28, v12, s41 bitop3:0x36
	v_bitop3_b32 v13, v29, v13, s41 bitop3:0x36
	v_bitop3_b32 v14, v30, v14, s41 bitop3:0x36
	v_bitop3_b32 v15, v31, v15, s41 bitop3:0x36
	v_bitop3_b32 v16, v32, v16, s41 bitop3:0x36
	v_bitop3_b32 v17, v33, v17, s41 bitop3:0x36
